# phase1 rmsnorm: norm weights preloaded once per workgroup into registers; per-column-step store+load vmcnt(0) drains removed
# speedup vs baseline: 1.0057x; 1.0057x over previous
.LBB0_78:
	s_or_b64 exec, exec, s[44:45]
	v_ashrrev_i32_e32 v109, 31, v108
	v_lshlrev_b64 v[0:1], 13, v[108:109]
	v_lshl_add_u64 v[114:115], v[110:111], 0, v[0:1]
	s_waitcnt lgkmcnt(0)
	s_barrier
	ds_read_b128 v[0:3], v127
	ds_read_b128 v[4:7], v127 offset:1024
	ds_read_b128 v[8:11], v127 offset:8192
	ds_read_b128 v[12:15], v127 offset:9216
	ds_read_b128 v[16:19], v127 offset:2048
	ds_read_b128 v[20:23], v127 offset:3072
	ds_read_b128 v[24:27], v127 offset:10240
	ds_read_b128 v[28:31], v127 offset:11264
	ds_read_b128 v[32:35], v127 offset:4096
	ds_read_b128 v[36:39], v127 offset:5120
	ds_read_b128 v[40:43], v127 offset:12288
	ds_read_b128 v[44:47], v127 offset:13312
	ds_read_b128 v[48:51], v127 offset:6144
	ds_read_b128 v[52:55], v127 offset:7168
	ds_read_b128 v[56:59], v127 offset:14336
	ds_read_b128 v[60:63], v127 offset:15360
	v_lshlrev_b64 v[64:65], 12, v[108:109]
	v_lshl_add_u64 v[116:117], v[112:113], 0, v[64:65]
	s_mov_b64 s[8:9], 0
	v_mov_b32_e32 v118, v140
	global_load_dwordx4 v[172:175], v[96:97], off
	global_load_dwordx4 v[176:179], v[96:97], off offset:1024
	global_load_dwordx4 v[180:183], v[96:97], off offset:2048
	global_load_dwordx4 v[184:187], v[96:97], off offset:3072
	global_load_dwordx4 v[188:191], v[98:99], off
	global_load_dwordx4 v[192:195], v[100:101], off
	global_load_dwordx4 v[196:199], v[102:103], off
	global_load_dwordx4 v[200:203], v[104:105], off
.LBB0_79:
	global_load_dwordx4 v[80:83], v[114:115], off offset:-4096
	global_load_dwordx4 v[84:87], v[114:115], off offset:-3072
	global_load_dwordx4 v[72:75], v[114:115], off
	global_load_dwordx4 v[68:71], v[114:115], off offset:1024
	global_load_dwordx4 v[76:79], v[114:115], off offset:2048
	global_load_dwordx4 v[64:67], v[114:115], off offset:3072
	global_load_dwordx4 v[142:145], v[114:115], off offset:-2048
	global_load_dwordx4 v[88:91], v[114:115], off offset:-1024
	v_lshl_add_u64 v[150:151], v[116:117], 0, s[8:9]
	s_movk_i32 s10, 0x1000
	s_add_u32 s8, s8, 0x2000
	s_addc_u32 s9, s9, 0
	s_cmpk_eq_u32 s8, 0x8000
	s_waitcnt vmcnt(7)
	v_mul_f32_e32 v109, v81, v81
	s_waitcnt vmcnt(6)
	v_mul_f32_e32 v119, v85, v85
	v_fmac_f32_e32 v109, v80, v80
	v_fmac_f32_e32 v119, v84, v84
	s_waitcnt vmcnt(5)
	v_mov_b32_e32 v154, v73
	s_waitcnt vmcnt(4)
	v_mov_b32_e32 v155, v69
	s_waitcnt vmcnt(1)
	v_mul_f32_e32 v170, v143, v143
	s_waitcnt vmcnt(0)
	v_mul_f32_e32 v171, v89, v89
	v_fmac_f32_e32 v170, v142, v142
	v_fmac_f32_e32 v109, v82, v82
	v_fmac_f32_e32 v119, v86, v86
	v_mov_b32_e32 v152, v72
	v_mov_b32_e32 v153, v68
	v_pk_mul_f32 v[154:155], v[154:155], v[154:155]
	v_fmac_f32_e32 v171, v88, v88
	v_fmac_f32_e32 v170, v144, v144
	v_fmac_f32_e32 v109, v83, v83
	v_fmac_f32_e32 v119, v87, v87
	v_mov_b32_e32 v158, v77
	v_mov_b32_e32 v159, v65
	v_mov_b32_e32 v160, v74
	v_mov_b32_e32 v161, v70
	v_pk_fma_f32 v[152:153], v[152:153], v[152:153], v[154:155]
	v_fmac_f32_e32 v171, v90, v90
	v_fmac_f32_e32 v170, v145, v145
	v_add_f32_e32 v109, v109, v119
	v_mov_b32_e32 v156, v76
	v_mov_b32_e32 v157, v64
	v_mov_b32_e32 v166, v75
	v_mov_b32_e32 v167, v71
	v_pk_mul_f32 v[158:159], v[158:159], v[158:159]
	v_pk_fma_f32 v[152:153], v[160:161], v[160:161], v[152:153]
	v_fmac_f32_e32 v171, v91, v91
	v_add_f32_e32 v109, v109, v170
	v_mov_b32_e32 v162, v78
	v_mov_b32_e32 v163, v66
	v_pk_fma_f32 v[154:155], v[156:157], v[156:157], v[158:159]
	v_pk_fma_f32 v[152:153], v[166:167], v[166:167], v[152:153]
	v_add_f32_e32 v109, v109, v171
	v_mov_b32_e32 v168, v79
	v_mov_b32_e32 v169, v67
	v_pk_fma_f32 v[154:155], v[162:163], v[162:163], v[154:155]
	v_add_f32_e32 v109, v109, v152
	v_pk_fma_f32 v[154:155], v[168:169], v[168:169], v[154:155]
	v_add_f32_e32 v109, v109, v153
	v_add_f32_e32 v109, v109, v154
	v_add_f32_e32 v109, v109, v155
	ds_bpermute_b32 v119, v121, v109
	s_waitcnt lgkmcnt(0)
	v_add_f32_e32 v109, v109, v119
	ds_bpermute_b32 v119, v122, v109
	s_waitcnt lgkmcnt(0)
	v_add_f32_e32 v109, v109, v119
	ds_bpermute_b32 v119, v123, v109
	s_waitcnt lgkmcnt(0)
	v_add_f32_e32 v109, v109, v119
	ds_bpermute_b32 v119, v124, v109
	s_waitcnt lgkmcnt(0)
	v_add_f32_e32 v109, v109, v119
	ds_bpermute_b32 v119, v125, v109
	s_waitcnt lgkmcnt(0)
	v_add_f32_e32 v109, v109, v119
	ds_bpermute_b32 v119, v126, v109
	s_waitcnt lgkmcnt(0)
	v_add_f32_e32 v109, v109, v119
	v_fmamk_f32 v109, v109, 0x3a000000, v141
	v_mul_f32_e32 v119, 0x4b800000, v109
	v_cmp_gt_f32_e32 vcc, s33, v109
	s_nop 1
	v_cndmask_b32_e32 v109, v109, v119, vcc
	v_rsq_f32_e32 v109, v109
	s_nop 0
	v_mul_f32_e32 v119, 0x45800000, v109
	v_cndmask_b32_e32 v152, v109, v119, vcc
	v_pk_mul_f32 v[80:81], v[80:81], v[152:153] op_sel_hi:[1,0]
	v_pk_mul_f32 v[82:83], v[82:83], v[152:153] op_sel_hi:[1,0]
	v_pk_mul_f32 v[80:81], v[172:173], v[80:81]
	v_pk_mul_f32 v[82:83], v[174:175], v[82:83]
	v_pk_fma_f32 v[80:81], v[8:9], v[80:81], v[0:1]
	v_pk_fma_f32 v[82:83], v[10:11], v[82:83], v[2:3]
	v_cvt_pk_bf16_f32 v80, v80, v81
	v_cvt_pk_bf16_f32 v81, v82, v83
	global_store_dwordx2 v[150:151], v[80:81], off
	v_pk_mul_f32 v[84:85], v[84:85], v[152:153] op_sel_hi:[1,0]
	v_pk_mul_f32 v[86:87], v[86:87], v[152:153] op_sel_hi:[1,0]
	v_pk_mul_f32 v[142:143], v[142:143], v[152:153] op_sel_hi:[1,0]
	v_pk_mul_f32 v[144:145], v[144:145], v[152:153] op_sel_hi:[1,0]
	v_pk_mul_f32 v[88:89], v[88:89], v[152:153] op_sel_hi:[1,0]
	v_pk_mul_f32 v[72:73], v[72:73], v[152:153] op_sel_hi:[1,0]
	v_pk_mul_f32 v[74:75], v[74:75], v[152:153] op_sel_hi:[1,0]
	v_pk_mul_f32 v[68:69], v[68:69], v[152:153] op_sel_hi:[1,0]
	v_pk_mul_f32 v[70:71], v[70:71], v[152:153] op_sel_hi:[1,0]
	v_ashrrev_i32_e32 v119, 31, v118
	v_pk_mul_f32 v[64:65], v[64:65], v[152:153] op_sel_hi:[1,0]
	v_pk_mul_f32 v[66:67], v[66:67], v[152:153] op_sel_hi:[1,0]
	v_lshlrev_b64 v[146:147], 12, v[118:119]
	v_pk_mul_f32 v[80:81], v[176:177], v[84:85]
	v_pk_mul_f32 v[82:83], v[178:179], v[86:87]
	v_pk_fma_f32 v[80:81], v[12:13], v[80:81], v[4:5]
	v_pk_fma_f32 v[82:83], v[14:15], v[82:83], v[6:7]
	v_cvt_pk_bf16_f32 v80, v80, v81
	v_cvt_pk_bf16_f32 v81, v82, v83
	global_store_dwordx2 v[150:151], v[80:81], off offset:512
	v_pk_mul_f32 v[84:85], v[90:91], v[152:153] op_sel_hi:[1,0]
	v_pk_mul_f32 v[80:81], v[180:181], v[142:143]
	v_pk_mul_f32 v[82:83], v[182:183], v[144:145]
	v_pk_fma_f32 v[80:81], v[24:25], v[80:81], v[16:17]
	v_pk_fma_f32 v[82:83], v[26:27], v[82:83], v[18:19]
	v_cvt_pk_bf16_f32 v80, v80, v81
	v_cvt_pk_bf16_f32 v81, v82, v83
	global_store_dwordx2 v[150:151], v[80:81], off offset:1024
	v_pk_mul_f32 v[80:81], v[184:185], v[88:89]
	v_pk_mul_f32 v[82:83], v[186:187], v[84:85]
	v_pk_fma_f32 v[80:81], v[80:81], v[28:29], v[20:21]
	v_pk_fma_f32 v[82:83], v[82:83], v[30:31], v[22:23]
	v_cvt_pk_bf16_f32 v80, v80, v81
	v_cvt_pk_bf16_f32 v81, v82, v83
	global_store_dwordx2 v[150:151], v[80:81], off offset:1536
	v_pk_mul_f32 v[72:73], v[72:73], v[188:189]
	v_pk_mul_f32 v[74:75], v[74:75], v[190:191]
	v_pk_fma_f32 v[72:73], v[72:73], v[40:41], v[32:33]
	v_pk_fma_f32 v[74:75], v[74:75], v[42:43], v[34:35]
	v_cvt_pk_bf16_f32 v72, v72, v73
	v_cvt_pk_bf16_f32 v73, v74, v75
	global_store_dwordx2 v[150:151], v[72:73], off offset:2048
	v_pk_mul_f32 v[68:69], v[68:69], v[192:193]
	v_pk_mul_f32 v[70:71], v[70:71], v[194:195]
	v_pk_fma_f32 v[68:69], v[68:69], v[44:45], v[36:37]
	v_pk_fma_f32 v[70:71], v[70:71], v[46:47], v[38:39]
	v_cvt_pk_bf16_f32 v68, v68, v69
	v_cvt_pk_bf16_f32 v69, v70, v71
	global_store_dwordx2 v[150:151], v[68:69], off offset:2560
	v_pk_mul_f32 v[72:73], v[76:77], v[152:153] op_sel_hi:[1,0]
	v_pk_mul_f32 v[74:75], v[78:79], v[152:153] op_sel_hi:[1,0]
	v_pk_mul_f32 v[68:69], v[72:73], v[196:197]
	v_pk_mul_f32 v[70:71], v[74:75], v[198:199]
	v_pk_fma_f32 v[68:69], v[68:69], v[56:57], v[48:49]
	v_pk_fma_f32 v[70:71], v[70:71], v[58:59], v[50:51]
	v_cvt_pk_bf16_f32 v68, v68, v69
	v_cvt_pk_bf16_f32 v69, v70, v71
	global_store_dwordx2 v[150:151], v[68:69], off offset:3072
	v_lshlrev_b64 v[72:73], 13, v[118:119]
	v_lshl_add_u64 v[72:73], v[94:95], 0, v[72:73]
	v_add_co_u32_e32 v74, vcc, s10, v72
	s_mov_b64 s[10:11], 0x4000
	s_nop 0
	v_addc_co_u32_e32 v75, vcc, 0, v73, vcc
	v_lshl_add_u64 v[114:115], v[114:115], 0, s[10:11]
	v_add_u32_e32 v118, 2, v118
	v_pk_mul_f32 v[64:65], v[64:65], v[200:201]
	v_pk_mul_f32 v[66:67], v[66:67], v[202:203]
	v_pk_fma_f32 v[64:65], v[64:65], v[60:61], v[52:53]
	v_pk_fma_f32 v[66:67], v[66:67], v[62:63], v[54:55]
	v_cvt_pk_bf16_f32 v64, v64, v65
	v_cvt_pk_bf16_f32 v65, v66, v67
	global_store_dwordx2 v[150:151], v[64:65], off offset:3584
	global_load_dwordx4 v[76:79], v[72:73], off
	global_load_dwordx4 v[68:71], v[74:75], off
	s_nop 0
	global_load_dwordx4 v[64:67], v[74:75], off offset:1024
	global_load_dwordx4 v[80:83], v[72:73], off offset:1024
	global_load_dwordx4 v[84:87], v[72:73], off offset:2048
	global_load_dwordx4 v[88:91], v[72:73], off offset:3072
	global_load_dwordx4 v[142:145], v[74:75], off offset:2048
	s_nop 0
	global_load_dwordx4 v[72:75], v[74:75], off offset:3072
	v_lshl_add_u64 v[150:151], v[106:107], 0, v[146:147]
	s_waitcnt vmcnt(7)
	v_mul_f32_e32 v109, v77, v77
	v_fmac_f32_e32 v109, v76, v76
	s_waitcnt vmcnt(6)
	v_mov_b32_e32 v154, v69
	s_waitcnt vmcnt(4)
	v_mul_f32_e32 v119, v81, v81
	s_waitcnt vmcnt(3)
	v_mul_f32_e32 v170, v85, v85
	v_fmac_f32_e32 v119, v80, v80
	v_mov_b32_e32 v155, v65
	s_waitcnt vmcnt(2)
	v_mul_f32_e32 v171, v89, v89
	v_fmac_f32_e32 v170, v84, v84
	v_fmac_f32_e32 v109, v78, v78
	v_fmac_f32_e32 v119, v82, v82
	v_mov_b32_e32 v152, v68
	v_mov_b32_e32 v153, v64
	v_pk_mul_f32 v[154:155], v[154:155], v[154:155]
	v_fmac_f32_e32 v171, v88, v88
	v_fmac_f32_e32 v170, v86, v86
	v_fmac_f32_e32 v109, v79, v79
	v_fmac_f32_e32 v119, v83, v83
	s_waitcnt vmcnt(1)
	v_mov_b32_e32 v158, v143
	s_waitcnt vmcnt(0)
	v_mov_b32_e32 v159, v73
	v_mov_b32_e32 v160, v70
	v_mov_b32_e32 v161, v66
	v_pk_fma_f32 v[152:153], v[152:153], v[152:153], v[154:155]
	v_fmac_f32_e32 v171, v90, v90
	v_fmac_f32_e32 v170, v87, v87
	v_add_f32_e32 v109, v109, v119
	v_mov_b32_e32 v156, v142
	v_mov_b32_e32 v157, v72
	v_mov_b32_e32 v166, v71
	v_mov_b32_e32 v167, v67
	v_pk_mul_f32 v[158:159], v[158:159], v[158:159]
	v_pk_fma_f32 v[152:153], v[160:161], v[160:161], v[152:153]
	v_fmac_f32_e32 v171, v91, v91
	v_add_f32_e32 v109, v109, v170
	v_mov_b32_e32 v162, v144
	v_mov_b32_e32 v163, v74
	v_pk_fma_f32 v[154:155], v[156:157], v[156:157], v[158:159]
	v_pk_fma_f32 v[152:153], v[166:167], v[166:167], v[152:153]
	v_add_f32_e32 v109, v109, v171
	v_mov_b32_e32 v168, v145
	v_mov_b32_e32 v169, v75
	v_pk_fma_f32 v[154:155], v[162:163], v[162:163], v[154:155]
	v_add_f32_e32 v109, v109, v152
	v_pk_fma_f32 v[154:155], v[168:169], v[168:169], v[154:155]
	v_add_f32_e32 v109, v109, v153
	v_add_f32_e32 v109, v109, v154
	v_add_f32_e32 v109, v109, v155
	ds_bpermute_b32 v119, v121, v109
	s_waitcnt lgkmcnt(0)
	v_add_f32_e32 v109, v109, v119
	ds_bpermute_b32 v119, v122, v109
	s_waitcnt lgkmcnt(0)
	v_add_f32_e32 v109, v109, v119
	ds_bpermute_b32 v119, v123, v109
	s_waitcnt lgkmcnt(0)
	v_add_f32_e32 v109, v109, v119
	ds_bpermute_b32 v119, v124, v109
	s_waitcnt lgkmcnt(0)
	v_add_f32_e32 v109, v109, v119
	ds_bpermute_b32 v119, v125, v109
	s_waitcnt lgkmcnt(0)
	v_add_f32_e32 v109, v109, v119
	ds_bpermute_b32 v119, v126, v109
	s_waitcnt lgkmcnt(0)
	v_add_f32_e32 v109, v109, v119
	v_fmamk_f32 v109, v109, 0x3a000000, v141
	v_mul_f32_e32 v119, 0x4b800000, v109
	v_cmp_gt_f32_e32 vcc, s33, v109
	s_nop 1
	v_cndmask_b32_e32 v109, v109, v119, vcc
	v_rsq_f32_e32 v109, v109
	s_nop 0
	v_mul_f32_e32 v119, 0x45800000, v109
	v_cndmask_b32_e32 v152, v109, v119, vcc
	v_pk_mul_f32 v[76:77], v[76:77], v[152:153] op_sel_hi:[1,0]
	v_pk_mul_f32 v[78:79], v[78:79], v[152:153] op_sel_hi:[1,0]
	v_pk_mul_f32 v[76:77], v[172:173], v[76:77]
	v_pk_mul_f32 v[78:79], v[174:175], v[78:79]
	v_pk_fma_f32 v[76:77], v[8:9], v[76:77], v[0:1]
	v_pk_fma_f32 v[78:79], v[10:11], v[78:79], v[2:3]
	v_cvt_pk_bf16_f32 v76, v76, v77
	v_cvt_pk_bf16_f32 v77, v78, v79
	global_store_dwordx2 v[150:151], v[76:77], off
	v_pk_mul_f32 v[80:81], v[80:81], v[152:153] op_sel_hi:[1,0]
	v_pk_mul_f32 v[82:83], v[82:83], v[152:153] op_sel_hi:[1,0]
	v_pk_mul_f32 v[68:69], v[68:69], v[152:153] op_sel_hi:[1,0]
	v_pk_mul_f32 v[70:71], v[70:71], v[152:153] op_sel_hi:[1,0]
	v_pk_mul_f32 v[64:65], v[64:65], v[152:153] op_sel_hi:[1,0]
	v_pk_mul_f32 v[66:67], v[66:67], v[152:153] op_sel_hi:[1,0]
	v_pk_mul_f32 v[76:77], v[176:177], v[80:81]
	v_pk_mul_f32 v[78:79], v[178:179], v[82:83]
	v_pk_fma_f32 v[76:77], v[12:13], v[76:77], v[4:5]
	v_pk_fma_f32 v[78:79], v[14:15], v[78:79], v[6:7]
	v_cvt_pk_bf16_f32 v76, v76, v77
	v_cvt_pk_bf16_f32 v77, v78, v79
	global_store_dwordx2 v[150:151], v[76:77], off offset:512
	v_pk_mul_f32 v[80:81], v[84:85], v[152:153] op_sel_hi:[1,0]
	v_pk_mul_f32 v[82:83], v[86:87], v[152:153] op_sel_hi:[1,0]
	v_pk_mul_f32 v[76:77], v[180:181], v[80:81]
	v_pk_mul_f32 v[78:79], v[182:183], v[82:83]
	v_pk_fma_f32 v[76:77], v[24:25], v[76:77], v[16:17]
	v_pk_fma_f32 v[78:79], v[26:27], v[78:79], v[18:19]
	v_cvt_pk_bf16_f32 v76, v76, v77
	v_cvt_pk_bf16_f32 v77, v78, v79
	global_store_dwordx2 v[150:151], v[76:77], off offset:1024
	v_pk_mul_f32 v[80:81], v[88:89], v[152:153] op_sel_hi:[1,0]
	v_pk_mul_f32 v[82:83], v[90:91], v[152:153] op_sel_hi:[1,0]
	v_pk_mul_f32 v[76:77], v[184:185], v[80:81]
	v_pk_mul_f32 v[78:79], v[186:187], v[82:83]
	v_pk_fma_f32 v[76:77], v[76:77], v[28:29], v[20:21]
	v_pk_fma_f32 v[78:79], v[78:79], v[30:31], v[22:23]
	v_cvt_pk_bf16_f32 v76, v76, v77
	v_cvt_pk_bf16_f32 v77, v78, v79
	global_store_dwordx2 v[150:151], v[76:77], off offset:1536
	v_pk_mul_f32 v[68:69], v[68:69], v[188:189]
	v_pk_mul_f32 v[70:71], v[70:71], v[190:191]
	v_pk_fma_f32 v[68:69], v[68:69], v[40:41], v[32:33]
	v_pk_fma_f32 v[70:71], v[70:71], v[42:43], v[34:35]
	v_cvt_pk_bf16_f32 v68, v68, v69
	v_cvt_pk_bf16_f32 v69, v70, v71
	global_store_dwordx2 v[150:151], v[68:69], off offset:2048
	v_pk_mul_f32 v[64:65], v[64:65], v[192:193]
	v_pk_mul_f32 v[66:67], v[66:67], v[194:195]
	v_pk_fma_f32 v[64:65], v[64:65], v[44:45], v[36:37]
	v_pk_fma_f32 v[66:67], v[66:67], v[46:47], v[38:39]
	v_cvt_pk_bf16_f32 v64, v64, v65
	v_cvt_pk_bf16_f32 v65, v66, v67
	global_store_dwordx2 v[150:151], v[64:65], off offset:2560
	v_pk_mul_f32 v[68:69], v[142:143], v[152:153] op_sel_hi:[1,0]
	v_pk_mul_f32 v[70:71], v[144:145], v[152:153] op_sel_hi:[1,0]
	v_pk_mul_f32 v[64:65], v[68:69], v[196:197]
	v_pk_mul_f32 v[66:67], v[70:71], v[198:199]
	v_pk_fma_f32 v[64:65], v[64:65], v[56:57], v[48:49]
	v_pk_fma_f32 v[66:67], v[66:67], v[58:59], v[50:51]
	v_cvt_pk_bf16_f32 v64, v64, v65
	v_cvt_pk_bf16_f32 v65, v66, v67
	global_store_dwordx2 v[150:151], v[64:65], off offset:3072
	v_pk_mul_f32 v[68:69], v[72:73], v[152:153] op_sel_hi:[1,0]
	v_pk_mul_f32 v[70:71], v[74:75], v[152:153] op_sel_hi:[1,0]
	v_pk_mul_f32 v[64:65], v[68:69], v[200:201]
	v_pk_mul_f32 v[66:67], v[70:71], v[202:203]
	v_pk_fma_f32 v[64:65], v[64:65], v[60:61], v[52:53]
	v_pk_fma_f32 v[66:67], v[66:67], v[62:63], v[54:55]
	v_cvt_pk_bf16_f32 v64, v64, v65
	v_cvt_pk_bf16_f32 v65, v66, v67
	global_store_dwordx2 v[150:151], v[64:65], off offset:3584
	s_cbranch_scc0 .LBB0_79
	s_add_i32 s38, s38, s72
	v_add_u32_e32 v140, s2, v140
	s_cmpk_gt_i32 s38, 0xff
	v_add_u32_e32 v108, s2, v108
	s_cbranch_scc0 .LBB0_66
